# placement flag cached in a VGPR (no reload/wait at P5 start and seam 2), on top of v22
# speedup vs baseline: 1.0113x; 1.0081x over previous
; #define LAS __attribute__((address_space(3)))
; __global__ void __launch_bounds__(NWAVES * 64, 2) mk_fwd(Args args) {
;     ...
;     if (IN(5)) {
;         if (F.G == 256) {
;             pg8::StaticOrder S; S.init(M, DM, F.G, (int)blockIdx.x); pg8::Unit u0; S.next(0, u0);
;             LAS float* tab = (LAS float*)(F.lds + TAB_OFF);
;             LateTab late{(unsigned*)(F.ctl + CW_LB + 2048 + 64 * u0.pm), bar.bar, (const float*)(ws + WS_SSQ) + u0.pm * 256, tab, F.wave,
;                          F.G == 256 && lo == 0 && hi == 7 && __hip_atomic_load((unsigned*)(F.ctl + CW_LB + 1024), RLX_AGENT) == 0u};
.LBB0_769:
	v_readlane_b32 s28, v252, 6
	v_readlane_b32 s29, v252, 7
	v_readlane_b32 s96, v252, 14
	s_cmp_lt_i32 s29, 6
	v_readlane_b32 s97, v252, 15
	v_readlane_b32 s71, v252, 13
	v_readlane_b32 s30, v252, 8
	v_readlane_b32 s31, v252, 9
	s_cbranch_scc1 .LBB0_834
	v_readlane_b32 s0, v252, 2
	s_cmpk_lg_i32 s0, 0x100
	s_cselect_b64 s[0:1], -1, 0
	s_cmp_lg_u32 s28, 0
	s_cselect_b64 s[2:3], -1, 0
	s_or_b64 s[0:1], s[2:3], s[0:1]
	s_cmp_lg_u32 s29, 7
	s_cselect_b64 s[2:3], -1, 0
	s_or_b64 s[2:3], s[0:1], s[2:3]
	s_mov_b64 s[0:1], 0
	s_and_b64 vcc, exec, s[2:3]
	s_cbranch_vccnz .LBB0_773
	v_mov_b32_e32 v0, 0x11000
	global_load_dword v0, v0, s[96:97] sc1
	s_mov_b64 s[0:1], -1
	s_waitcnt vmcnt(0)
	v_mov_b32_e32 v253, v0
	v_cmp_ne_u32_e64 s[2:3], 0, v0
	s_andn2_b64 vcc, exec, s[2:3]
	s_cbranch_vccz .LBB0_774

; __global__ void __launch_bounds__(NWAVES * 64, 2) mk_fwd(Args args) {
;     ...
;             LateTab late{(unsigned*)(F.ctl + CW_LB + 2048 + 64 * u0.pm), bar.bar, (const float*)(ws + WS_SSQ) + u0.pm * 256, tab, F.wave,
;                          F.G == 256 && lo == 0 && hi == 7 && __hip_atomic_load((unsigned*)(F.ctl + CW_LB + 1024), RLX_AGENT) == 0u};
.LBB0_842:
	s_cmp_eq_u32 s28, 0
	s_cselect_b64 s[0:1], -1, 0
	s_cmp_eq_u32 s29, 7
	s_cselect_b64 s[4:5], -1, 0
	s_and_b64 s[0:1], s[0:1], s[4:5]
	s_andn2_b64 vcc, exec, s[0:1]
	s_mov_b64 s[0:1], 0
	s_cbranch_vccnz .LBB0_844
	v_mov_b32_e32 v0, v253
	v_cmp_eq_u32_e64 s[0:1], 0, v0

; __device__ __forceinline__ unsigned xb_ld(unsigned* p)              { return __hip_atomic_load(p, __ATOMIC_RELAXED, __HIP_MEMORY_SCOPE_AGENT); }
; #define XB_SPIN(cond, bar) do { unsigned _sp = 0; while (cond) { __builtin_amdgcn_s_sleep(1); \
;     if ((++_sp & 255u) == 0u) { if (xb_ld(&(bar)[XB_TMO])) break; if (_sp > XB_SPIN_CAP) { atomicAdd(&(bar)[XB_TMO], 1u); break; } } } } while (0)
; __device__ __forceinline__ bool xb_thread0(int wave) { return wave == 0 && hw_lane() == 0; }
; #define BOTH(k) (IN(k) && IN((k) + 1))
; __global__ void __launch_bounds__(NWAVES * 64, 2) mk_fwd(Args args) {
;     ...
;         if (BOTH(5)) {
;             if (F.G == 256 && lo == 0 && hi == 7 && __hip_atomic_load((unsigned*)(F.ctl + CW_LB + 1024), RLX_AGENT) == 0u) {
;                 asm volatile("s_waitcnt vmcnt(0)" ::: "memory"); __syncthreads();
;                 if (xb_thread0(F.wave)) { unsigned* cnt_ = (unsigned*)(F.ctl + CW_LB + 2048 + 64 * (8 * (F.vcu >> 5) + (F.vcu & 7))); XB_SPIN(xb_ld(cnt_) < 8u, bar.bar);
.LBB0_889:
	s_cmp_lt_i32 s29, 7
	s_cbranch_scc1 .LBB0_968
	s_cmp_lg_u32 s28, 0
	s_cselect_b64 s[0:1], -1, 0
	s_xor_b64 s[2:3], s[2:3], -1
	s_or_b64 s[0:1], s[0:1], s[2:3]
	s_cmp_lg_u32 s29, 7
	s_cselect_b64 s[2:3], -1, 0
	s_or_b64 s[2:3], s[0:1], s[2:3]
	s_mov_b64 s[0:1], 0
	s_and_b64 vcc, exec, s[2:3]
	s_cbranch_vccnz .LBB0_893
	v_mov_b32_e32 v0, v253
	s_mov_b64 s[0:1], -1
	s_waitcnt vmcnt(0)
	v_cmp_ne_u32_e64 s[2:3], 0, v0
	s_andn2_b64 vcc, exec, s[2:3]
	s_cbranch_vccz .LBB0_894

; __global__ void __launch_bounds__(NWAVES * 64, 2) mk_fwd(Args args) {
	.amdhsa_kernel _Z6mk_fwd4Args
		.amdhsa_group_segment_fixed_size 0
		.amdhsa_private_segment_fixed_size 0
		.amdhsa_kernarg_size 440
		.amdhsa_user_sgpr_count 2
		.amdhsa_user_sgpr_dispatch_ptr 0
		.amdhsa_user_sgpr_queue_ptr 0
		.amdhsa_user_sgpr_kernarg_segment_ptr 1
		.amdhsa_user_sgpr_dispatch_id 0
		.amdhsa_user_sgpr_kernarg_preload_length 0
		.amdhsa_user_sgpr_kernarg_preload_offset 0
		.amdhsa_user_sgpr_private_segment_size 0
		.amdhsa_uses_dynamic_stack 0
		.amdhsa_enable_private_segment 0
		.amdhsa_system_sgpr_workgroup_id_x 1
		.amdhsa_system_sgpr_workgroup_id_y 0
		.amdhsa_system_sgpr_workgroup_id_z 0
		.amdhsa_system_sgpr_workgroup_info 0
		.amdhsa_system_vgpr_workitem_id 0
		.amdhsa_next_free_vgpr 254
		.amdhsa_next_free_sgpr 102
		.amdhsa_accum_offset 256
		.amdhsa_reserve_vcc 1
		.amdhsa_float_round_mode_32 0
		.amdhsa_float_round_mode_16_64 0
		.amdhsa_float_denorm_mode_32 3
		.amdhsa_float_denorm_mode_16_64 3
		.amdhsa_dx10_clamp 1
		.amdhsa_ieee_mode 1
		.amdhsa_fp16_overflow 0
		.amdhsa_tg_split 0
		.amdhsa_exception_fp_ieee_invalid_op 0
		.amdhsa_exception_fp_denorm_src 0
		.amdhsa_exception_fp_ieee_div_zero 0
		.amdhsa_exception_fp_ieee_overflow 0
		.amdhsa_exception_fp_ieee_underflow 0
		.amdhsa_exception_fp_ieee_inexact 0
		.amdhsa_exception_int_div_zero 0
	.end_amdhsa_kernel

; __global__ void __launch_bounds__(NWAVES * 64, 2) mk_fwd(Args args) {
.Lfunc_end0:
	.size	_Z6mk_fwd4Args, .Lfunc_end0-_Z6mk_fwd4Args
	.set _Z6mk_fwd4Args.num_vgpr, 254
	.set _Z6mk_fwd4Args.num_agpr, 0
	.set _Z6mk_fwd4Args.numbered_sgpr, 102
	.set _Z6mk_fwd4Args.num_named_barrier, 0
	.set _Z6mk_fwd4Args.private_seg_size, 0
	.set _Z6mk_fwd4Args.uses_vcc, 1
	.set _Z6mk_fwd4Args.uses_flat_scratch, 0
	.set _Z6mk_fwd4Args.has_dyn_sized_stack, 0
	.set _Z6mk_fwd4Args.has_recursion, 0
	.set _Z6mk_fwd4Args.has_indirect_call, 0

; __global__ void __launch_bounds__(NWAVES * 64, 2) mk_fwd(Args args) {
amdhsa.kernels:
  - .agpr_count:     0
    .args:
      - .offset:         0
        .size:           184
        .value_kind:     by_value
      - .offset:         184
        .size:           4
        .value_kind:     hidden_block_count_x
      - .offset:         188
        .size:           4
        .value_kind:     hidden_block_count_y
      - .offset:         192
        .size:           4
        .value_kind:     hidden_block_count_z
      - .offset:         196
        .size:           2
        .value_kind:     hidden_group_size_x
      - .offset:         198
        .size:           2
        .value_kind:     hidden_group_size_y
      - .offset:         200
        .size:           2
        .value_kind:     hidden_group_size_z
      - .offset:         202
        .size:           2
        .value_kind:     hidden_remainder_x
      - .offset:         204
        .size:           2
        .value_kind:     hidden_remainder_y
      - .offset:         206
        .size:           2
        .value_kind:     hidden_remainder_z
      - .offset:         224
        .size:           8
        .value_kind:     hidden_global_offset_x
      - .offset:         232
        .size:           8
        .value_kind:     hidden_global_offset_y
      - .offset:         240
        .size:           8
        .value_kind:     hidden_global_offset_z
      - .offset:         248
        .size:           2
        .value_kind:     hidden_grid_dims
      - .offset:         304
        .size:           4
        .value_kind:     hidden_dynamic_lds_size
    .group_segment_fixed_size: 0
    .kernarg_segment_align: 8
    .kernarg_segment_size: 440
    .language:       OpenCL C
    .language_version:
      - 2
      - 0
    .max_flat_workgroup_size: 512
    .name:           _Z6mk_fwd4Args
    .private_segment_fixed_size: 0
    .sgpr_count:     108
    .sgpr_spill_count: 51
    .symbol:         _Z6mk_fwd4Args.kd
    .uniform_work_group_size: 1
    .uses_dynamic_stack: false
    .vgpr_count:     254
    .vgpr_spill_count: 0
    .wavefront_size: 64
